# attention next-tile K/V addresses: med3 clamp + 24-bit mad + SGPR-base global loads (80 fewer VALU per tile)
# speedup vs baseline: 1.0397x; 1.0010x over previous
; #define LAS __attribute__((address_space(3)))
; #define ATT_LOAD_KV(t_) do { _Pragma("unroll") for (int i = 0; i < 8; ++i) { int vi = a0 - 64 + 32 * (t_) + 4 * i + (lane >> 4); vi = vi < 0 ? 0 : (vi > L - 1 ? L - 1 : vi); \
;         const size_t go = (size_t)(r + d * vi) * 1024 + h * 128 + (lane & 15) * 8; kr[i] = *(const u32x4*)(Kb + go); vr[i] = *(const u32x4*)(V + go); } } while (0)
; __device__ __forceinline__ void attn_wave_unit(LAS unsigned char* wl, const bf16* __restrict__ Q, const bf16* __restrict__ Kb, const bf16* __restrict__ V, const float* ssq_x, const float* ssq_qk, ...
;     ...
;     for (int t = 0; t < 5; ++t) {
;         const int kb = a0 - 64 + 32 * t;
; #pragma unroll
;         for (int i = 0; i < 8; ++i) { *(LAS u32x4*)(wl + K_OFF + (4 * i + (lane >> 4)) * KPITCH + (lane & 15) * 16) = kr[i];
;                                       *(LAS u32x4*)(wl + (4 * i + (lane >> 4)) * VPITCH + (lane & 15) * 16) = vr[i]; }
;         if (t < 4) ATT_LOAD_KV(t + 1);
.LBB0_521:
	s_cmpk_eq_i32 s40, 0x80
	s_waitcnt vmcnt(0)
	ds_write_b128 v238, v[130:133] offset:10240
	ds_write_b128 v236, v[134:137]
	ds_write_b128 v238, v[138:141] offset:11328
	ds_write_b128 v236, v[142:145] offset:1280
	ds_write_b128 v238, v[146:149] offset:12416
	ds_write_b128 v236, v[150:153] offset:2560
	ds_write_b128 v238, v[154:157] offset:13504
	ds_write_b128 v236, v[158:161] offset:3840
	ds_write_b128 v238, v[162:165] offset:14592
	ds_write_b128 v236, v[166:169] offset:5120
	s_waitcnt vmcnt(0) lgkmcnt(0)
	ds_write_b128 v238, v[170:173] offset:15680
	ds_write_b128 v236, v[174:177] offset:6400
	ds_write_b128 v238, v[178:181] offset:16768
	ds_write_b128 v236, v[182:185] offset:7680
	ds_write_b128 v238, v[186:189] offset:17856
	ds_write_b128 v236, v[190:193] offset:8960
	s_cbranch_scc1 .LBB0_523
	v_add_u32_e32 v68, s40, v96
	s_lshl_b32 vcc_lo, s92, 11
	v_lshl_add_u32 v65, s91, 11, v241
	v_subrev_u32_e32 v64, 32, v68
	v_med3_i32 v64, v64, 0, v240
	v_mad_u32_u24 v66, v64, vcc_lo, v65
	global_load_dwordx4 v[130:133], v66, s[70:71]
	global_load_dwordx4 v[134:137], v66, s[78:79]
	v_subrev_u32_e32 v64, 28, v68
	v_med3_i32 v64, v64, 0, v240
	v_mad_u32_u24 v66, v64, vcc_lo, v65
	global_load_dwordx4 v[138:141], v66, s[70:71]
	global_load_dwordx4 v[142:145], v66, s[78:79]
	v_subrev_u32_e32 v64, 24, v68
	v_med3_i32 v64, v64, 0, v240
	v_mad_u32_u24 v66, v64, vcc_lo, v65
	global_load_dwordx4 v[146:149], v66, s[70:71]
	global_load_dwordx4 v[150:153], v66, s[78:79]
	v_subrev_u32_e32 v64, 20, v68
	v_med3_i32 v64, v64, 0, v240
	v_mad_u32_u24 v66, v64, vcc_lo, v65
	global_load_dwordx4 v[154:157], v66, s[70:71]
	global_load_dwordx4 v[158:161], v66, s[78:79]
	v_add_u32_e32 v64, -16, v68
	v_med3_i32 v64, v64, 0, v240
	v_mad_u32_u24 v66, v64, vcc_lo, v65
	global_load_dwordx4 v[162:165], v66, s[70:71]
	global_load_dwordx4 v[166:169], v66, s[78:79]
	v_add_u32_e32 v64, -12, v68
	v_med3_i32 v64, v64, 0, v240
	v_mad_u32_u24 v66, v64, vcc_lo, v65
	global_load_dwordx4 v[170:173], v66, s[70:71]
	global_load_dwordx4 v[174:177], v66, s[78:79]
	v_add_u32_e32 v64, -8, v68
	v_med3_i32 v64, v64, 0, v240
	v_mad_u32_u24 v66, v64, vcc_lo, v65
	global_load_dwordx4 v[178:181], v66, s[70:71]
	global_load_dwordx4 v[182:185], v66, s[78:79]
	v_add_u32_e32 v64, -4, v68
	v_med3_i32 v64, v64, 0, v240
	v_mad_u32_u24 v66, v64, vcc_lo, v65
	global_load_dwordx4 v[186:189], v66, s[70:71]
	global_load_dwordx4 v[190:193], v66, s[78:79]
